# pp_v21 + seams: acquire-side buffer_inv sc1 issued with the arrival atomic (before polling) instead of after the poll
# speedup vs baseline: 1.0090x; 1.0090x over previous
.LBB0_510:
	s_cmp_gt_i32 s83, 2
	s_cselect_b64 s[0:1], -1, 0
	s_and_b64 s[4:5], s[10:11], s[0:1]
	v_readlane_b32 s38, v238, 36
	s_andn2_b64 vcc, exec, s[4:5]
	v_readlane_b32 s39, v238, 37
	s_mov_b32 s40, s92
	s_cbranch_vccnz .LBB0_564
	s_waitcnt vmcnt(0)
	s_waitcnt vmcnt(0)
	s_barrier
	s_and_saveexec_b64 s[4:5], s[38:39]
	s_cbranch_execz .LBB0_563
	s_add_u32 s98, s98, 1
	v_mov_b32_e32 v1, 0x25f20
	ds_read_b64 v[2:3], v1
	v_readlane_b32 s6, v238, 18
	v_readlane_b32 s7, v238, 19
	s_lshl_b32 s2, s87, 8
	s_addk_i32 s2, 0x1400
	v_mov_b32_e32 v1, s2
	v_mov_b32_e32 v5, 1
	s_nop 1
	global_atomic_add v1, v1, v5, s[6:7] sc0
	buffer_inv sc1
	s_waitcnt vmcnt(1) lgkmcnt(0)
	v_readfirstlane_b32 s12, v1
	v_readfirstlane_b32 s9, v2
	v_readfirstlane_b32 s10, v3
	s_add_u32 s12, s12, 1
	s_mul_i32 s9, s9, s98
	s_mul_i32 s10, s10, s98
	v_mov_b32_e32 v1, 0x3400
	s_cmp_eq_u32 s12, s9
	s_cbranch_scc0 .Lfs0_spin
	buffer_wbl2 sc1
	s_waitcnt vmcnt(0)
	global_atomic_add v1, v5, s[6:7]

.Lfs0_loop:
	global_load_dword v2, v1, s[6:7] sc1
	s_add_u32 s11, s11, 1
	s_waitcnt vmcnt(0)
	v_readfirstlane_b32 s12, v2
	s_cmp_ge_u32 s12, s10
	s_cbranch_scc1 .Lfs0_done
	s_sleep 1
	s_cmp_lt_u32 s11, 0x100000
	s_cbranch_scc1 .Lfs0_loop
.Lfs0_done:
	s_waitcnt vmcnt(0)
.LBB0_563:
	s_or_b64 exec, exec, s[4:5]
	s_waitcnt lgkmcnt(0)
	s_barrier

.LBB0_855:
	s_cmp_gt_i32 s83, 4
	s_cselect_b64 s[0:1], -1, 0
	s_and_b64 s[4:5], s[6:7], s[0:1]
	s_andn2_b64 vcc, exec, s[4:5]
	s_cbranch_vccnz .LBB0_909
	s_waitcnt vmcnt(0)
	s_waitcnt vmcnt(0) lgkmcnt(0)
	s_barrier
	s_and_saveexec_b64 s[4:5], s[38:39]
	s_cbranch_execz .LBB0_908
	s_add_u32 s98, s98, 1
	v_mov_b32_e32 v1, 0x25f20
	ds_read_b64 v[2:3], v1
	v_readlane_b32 s6, v238, 18
	v_readlane_b32 s7, v238, 19
	s_lshl_b32 s2, s87, 8
	s_addk_i32 s2, 0x1400
	v_mov_b32_e32 v1, s2
	v_mov_b32_e32 v5, 1
	s_nop 1
	global_atomic_add v1, v1, v5, s[6:7] sc0
	buffer_inv sc1
	s_waitcnt vmcnt(1) lgkmcnt(0)
	v_readfirstlane_b32 s12, v1
	v_readfirstlane_b32 s9, v2
	v_readfirstlane_b32 s10, v3
	s_add_u32 s12, s12, 1
	s_mul_i32 s9, s9, s98
	s_mul_i32 s10, s10, s98
	v_mov_b32_e32 v1, 0x3400
	s_cmp_eq_u32 s12, s9
	s_cbranch_scc0 .Lfs1_spin
	buffer_wbl2 sc1
	s_waitcnt vmcnt(0)
	global_atomic_add v1, v5, s[6:7]

.Lfs1_loop:
	global_load_dword v2, v1, s[6:7] sc1
	s_add_u32 s11, s11, 1
	s_waitcnt vmcnt(0)
	v_readfirstlane_b32 s12, v2
	s_cmp_ge_u32 s12, s10
	s_cbranch_scc1 .Lfs1_done
	s_sleep 1
	s_cmp_lt_u32 s11, 0x100000
	s_cbranch_scc1 .Lfs1_loop
.Lfs1_done:
	s_waitcnt vmcnt(0)
.LBB0_908:
	s_or_b64 exec, exec, s[4:5]
	s_waitcnt lgkmcnt(0)
	s_barrier

.LBB0_959:
	s_cmp_gt_i32 s83, 7
	s_cselect_b64 s[4:5], -1, 0
	s_and_b64 s[0:1], s[0:1], s[4:5]
	s_andn2_b64 vcc, exec, s[0:1]
	s_cbranch_vccnz .LBB0_1013
	s_waitcnt vmcnt(0)
	s_waitcnt vmcnt(0) lgkmcnt(0)
	s_barrier
	s_and_saveexec_b64 s[0:1], s[38:39]
	s_cbranch_execz .LBB0_1012
	s_add_u32 s98, s98, 1
	v_mov_b32_e32 v1, 0x25f20
	ds_read_b64 v[2:3], v1
	v_readlane_b32 s6, v238, 18
	v_readlane_b32 s7, v238, 19
	s_lshl_b32 s2, s87, 8
	s_addk_i32 s2, 0x1400
	v_mov_b32_e32 v1, s2
	v_mov_b32_e32 v5, 1
	s_nop 1
	global_atomic_add v1, v1, v5, s[6:7] sc0
	buffer_inv sc1
	s_waitcnt vmcnt(1) lgkmcnt(0)
	v_readfirstlane_b32 s12, v1
	v_readfirstlane_b32 s9, v2
	v_readfirstlane_b32 s10, v3
	s_add_u32 s12, s12, 1
	s_mul_i32 s9, s9, s98
	s_mul_i32 s10, s10, s98
	v_mov_b32_e32 v1, 0x3400
	s_cmp_eq_u32 s12, s9
	s_cbranch_scc0 .Lfs2_spin
	buffer_wbl2 sc1
	s_waitcnt vmcnt(0)
	global_atomic_add v1, v5, s[6:7]

.Lfs2_loop:
	global_load_dword v2, v1, s[6:7] sc1
	s_add_u32 s11, s11, 1
	s_waitcnt vmcnt(0)
	v_readfirstlane_b32 s12, v2
	s_cmp_ge_u32 s12, s10
	s_cbranch_scc1 .Lfs2_done
	s_sleep 1
	s_cmp_lt_u32 s11, 0x100000
	s_cbranch_scc1 .Lfs2_loop
.Lfs2_done:
	s_waitcnt vmcnt(0)
.LBB0_1012:
	s_or_b64 exec, exec, s[0:1]
	s_waitcnt lgkmcnt(0)
	s_barrier

.LBB0_1147:
	s_barrier
	s_waitcnt vmcnt(0)
	v_readlane_b32 s38, v238, 36
	v_readlane_b32 s39, v238, 37
	s_barrier
	s_and_saveexec_b64 s[0:1], s[38:39]
	v_readlane_b32 s86, v238, 47
	v_readlane_b32 s87, v238, 46
	v_readlane_b32 s40, v238, 58
	v_readlane_b32 s93, v238, 48
	v_readlane_b32 s24, v238, 38
	v_readlane_b32 s41, v238, 59
	s_cbranch_execz .LBB0_1199
	s_add_u32 s98, s98, 1
	v_mov_b32_e32 v1, 0x25f20
	ds_read_b64 v[2:3], v1
	v_readlane_b32 s6, v238, 18
	v_readlane_b32 s7, v238, 19
	s_lshl_b32 s2, s87, 8
	s_addk_i32 s2, 0x1400
	v_mov_b32_e32 v1, s2
	v_mov_b32_e32 v5, 1
	s_nop 1
	global_atomic_add v1, v1, v5, s[6:7] sc0
	buffer_inv sc1
	s_waitcnt vmcnt(1) lgkmcnt(0)
	v_readfirstlane_b32 s12, v1
	v_readfirstlane_b32 s9, v2
	v_readfirstlane_b32 s10, v3
	s_add_u32 s12, s12, 1
	s_mul_i32 s9, s9, s98
	s_mul_i32 s10, s10, s98
	v_mov_b32_e32 v1, 0x3400
	s_cmp_eq_u32 s12, s9
	s_cbranch_scc0 .Lfs3_spin
	buffer_wbl2 sc1
	s_waitcnt vmcnt(0)
	global_atomic_add v1, v5, s[6:7]

.Lfs3_loop:
	global_load_dword v2, v1, s[6:7] sc1
	s_add_u32 s11, s11, 1
	s_waitcnt vmcnt(0)
	v_readfirstlane_b32 s12, v2
	s_cmp_ge_u32 s12, s10
	s_cbranch_scc1 .Lfs3_done
	s_sleep 1
	s_cmp_lt_u32 s11, 0x100000
	s_cbranch_scc1 .Lfs3_loop
.Lfs3_done:
	s_waitcnt vmcnt(0)
.LBB0_1199:
	s_or_b64 exec, exec, s[0:1]
	s_waitcnt lgkmcnt(0)
	s_barrier
	s_barrier
	s_and_saveexec_b64 s[0:1], s[38:39]
	s_cbranch_execz .LBB0_1201
	s_add_i32 s2, 0, 0x25e20
	v_mov_b32_e32 v1, 0
	s_waitcnt vmcnt(2)
	v_mov_b32_e32 v2, s2
	ds_write_b32 v2, v1

.LBB0_1221:
	s_cmp_gt_i32 s83, 8
	s_cselect_b64 s[0:1], -1, 0
	s_and_b64 s[4:5], s[4:5], s[0:1]
	s_andn2_b64 vcc, exec, s[4:5]
	s_mov_b64 s[60:61], s[38:39]
	s_cbranch_vccnz .LBB0_1275
	s_waitcnt vmcnt(0)
	s_waitcnt vmcnt(0) lgkmcnt(0)
	s_barrier
	s_and_saveexec_b64 s[4:5], s[38:39]
	s_cbranch_execz .LBB0_1274
	s_add_u32 s98, s98, 1
	v_mov_b32_e32 v1, 0x25f20
	ds_read_b64 v[2:3], v1
	v_readlane_b32 s6, v238, 18
	v_readlane_b32 s7, v238, 19
	s_lshl_b32 s2, s87, 8
	s_addk_i32 s2, 0x1400
	v_mov_b32_e32 v1, s2
	v_mov_b32_e32 v5, 1
	s_nop 1
	global_atomic_add v1, v1, v5, s[6:7] sc0
	buffer_inv sc1
	s_waitcnt vmcnt(1) lgkmcnt(0)
	v_readfirstlane_b32 s12, v1
	v_readfirstlane_b32 s9, v2
	v_readfirstlane_b32 s10, v3
	s_add_u32 s12, s12, 1
	s_mul_i32 s9, s9, s98
	s_mul_i32 s10, s10, s98
	v_mov_b32_e32 v1, 0x3400
	s_cmp_eq_u32 s12, s9
	s_cbranch_scc0 .Lfs4_spin
	buffer_wbl2 sc1
	s_waitcnt vmcnt(0)
	global_atomic_add v1, v5, s[6:7]

.Lfs4_loop:
	global_load_dword v2, v1, s[6:7] sc1
	s_add_u32 s11, s11, 1
	s_waitcnt vmcnt(0)
	v_readfirstlane_b32 s12, v2
	s_cmp_ge_u32 s12, s10
	s_cbranch_scc1 .Lfs4_done
	s_sleep 1
	s_cmp_lt_u32 s11, 0x100000
	s_cbranch_scc1 .Lfs4_loop
.Lfs4_done:
	s_waitcnt vmcnt(0)
.LBB0_1274:
	s_or_b64 exec, exec, s[4:5]
	s_waitcnt lgkmcnt(0)
	s_barrier

.LBB0_1279:
	s_cmp_gt_i32 s83, 9
	s_cselect_b64 s[0:1], -1, 0
	s_and_b64 s[4:5], s[6:7], s[0:1]
	s_andn2_b64 vcc, exec, s[4:5]
	s_cbranch_vccnz .LBB0_1333
	s_waitcnt vmcnt(0)
	s_waitcnt vmcnt(0) lgkmcnt(0)
	s_barrier
	s_and_saveexec_b64 s[4:5], s[38:39]
	s_cbranch_execz .LBB0_1332
	s_add_u32 s98, s98, 1
	v_mov_b32_e32 v1, 0x25f20
	ds_read_b64 v[2:3], v1
	v_readlane_b32 s6, v238, 18
	v_readlane_b32 s7, v238, 19
	s_lshl_b32 s2, s87, 8
	s_addk_i32 s2, 0x1400
	v_mov_b32_e32 v1, s2
	v_mov_b32_e32 v5, 1
	s_nop 1
	global_atomic_add v1, v1, v5, s[6:7] sc0
	buffer_inv sc1
	s_waitcnt vmcnt(1) lgkmcnt(0)
	v_readfirstlane_b32 s12, v1
	v_readfirstlane_b32 s9, v2
	v_readfirstlane_b32 s10, v3
	s_add_u32 s12, s12, 1
	s_mul_i32 s9, s9, s98
	s_mul_i32 s10, s10, s98
	v_mov_b32_e32 v1, 0x3400
	s_cmp_eq_u32 s12, s9
	s_cbranch_scc0 .Lfs5_spin
	buffer_wbl2 sc1
	s_waitcnt vmcnt(0)
	global_atomic_add v1, v5, s[6:7]

.Lfs5_loop:
	global_load_dword v2, v1, s[6:7] sc1
	s_add_u32 s11, s11, 1
	s_waitcnt vmcnt(0)
	v_readfirstlane_b32 s12, v2
	s_cmp_ge_u32 s12, s10
	s_cbranch_scc1 .Lfs5_done
	s_sleep 1
	s_cmp_lt_u32 s11, 0x100000
	s_cbranch_scc1 .Lfs5_loop
.Lfs5_done:
	s_waitcnt vmcnt(0)
.LBB0_1332:
	s_or_b64 exec, exec, s[4:5]
	s_waitcnt lgkmcnt(0)
	s_barrier

.LBB0_1360:
	s_cmp_lt_i32 s82, 11
	s_cselect_b64 s[4:5], -1, 0
	s_cmp_gt_i32 s83, 11
	s_cselect_b64 s[0:1], -1, 0
	s_and_b64 s[4:5], s[4:5], s[0:1]
	s_andn2_b64 vcc, exec, s[4:5]
	s_cbranch_vccnz .LBB0_1414
	s_waitcnt vmcnt(0)
	s_waitcnt vmcnt(0) lgkmcnt(0)
	s_barrier
	s_and_saveexec_b64 s[4:5], s[38:39]
	s_cbranch_execz .LBB0_1413
	s_add_u32 s98, s98, 1
	v_mov_b32_e32 v1, 0x25f20
	ds_read_b64 v[2:3], v1
	v_readlane_b32 s6, v238, 18
	v_readlane_b32 s7, v238, 19
	s_lshl_b32 s2, s87, 8
	s_addk_i32 s2, 0x1400
	v_mov_b32_e32 v1, s2
	v_mov_b32_e32 v5, 1
	s_nop 1
	global_atomic_add v1, v1, v5, s[6:7] sc0
	buffer_inv sc1
	s_waitcnt vmcnt(1) lgkmcnt(0)
	v_readfirstlane_b32 s12, v1
	v_readfirstlane_b32 s9, v2
	v_readfirstlane_b32 s10, v3
	s_add_u32 s12, s12, 1
	s_mul_i32 s9, s9, s98
	s_mul_i32 s10, s10, s98
	v_mov_b32_e32 v1, 0x3400
	s_cmp_eq_u32 s12, s9
	s_cbranch_scc0 .Lfs6_spin
	buffer_wbl2 sc1
	s_waitcnt vmcnt(0)
	global_atomic_add v1, v5, s[6:7]

.Lfs6_loop:
	global_load_dword v2, v1, s[6:7] sc1
	s_add_u32 s11, s11, 1
	s_waitcnt vmcnt(0)
	v_readfirstlane_b32 s12, v2
	s_cmp_ge_u32 s12, s10
	s_cbranch_scc1 .Lfs6_done
	s_sleep 1
	s_cmp_lt_u32 s11, 0x100000
	s_cbranch_scc1 .Lfs6_loop
.Lfs6_done:
	s_waitcnt vmcnt(0)
.LBB0_1413:
	s_or_b64 exec, exec, s[4:5]
	s_waitcnt lgkmcnt(0)
	s_barrier

.LBB0_1457:
	s_cmp_gt_i32 s83, 12
	s_cselect_b64 s[0:1], -1, 0
	s_and_b64 s[4:5], s[6:7], s[0:1]
	s_andn2_b64 vcc, exec, s[4:5]
	s_cbranch_vccnz .LBB0_1511
	s_waitcnt vmcnt(0)
	s_waitcnt vmcnt(0) lgkmcnt(0)
	s_barrier
	s_and_saveexec_b64 s[4:5], s[38:39]
	s_cbranch_execz .LBB0_1510
	s_add_u32 s98, s98, 1
	v_mov_b32_e32 v1, 0x25f20
	ds_read_b64 v[2:3], v1
	v_readlane_b32 s6, v238, 18
	v_readlane_b32 s7, v238, 19
	s_lshl_b32 s2, s87, 8
	s_addk_i32 s2, 0x1400
	v_mov_b32_e32 v1, s2
	v_mov_b32_e32 v5, 1
	s_nop 1
	global_atomic_add v1, v1, v5, s[6:7] sc0
	buffer_inv sc1
	s_waitcnt vmcnt(1) lgkmcnt(0)
	v_readfirstlane_b32 s12, v1
	v_readfirstlane_b32 s9, v2
	v_readfirstlane_b32 s10, v3
	s_add_u32 s12, s12, 1
	s_mul_i32 s9, s9, s98
	s_mul_i32 s10, s10, s98
	v_mov_b32_e32 v1, 0x3400
	s_cmp_eq_u32 s12, s9
	s_cbranch_scc0 .Lfs7_spin
	buffer_wbl2 sc1
	s_waitcnt vmcnt(0)
	global_atomic_add v1, v5, s[6:7]

.Lfs7_loop:
	global_load_dword v2, v1, s[6:7] sc1
	s_add_u32 s11, s11, 1
	s_waitcnt vmcnt(0)
	v_readfirstlane_b32 s12, v2
	s_cmp_ge_u32 s12, s10
	s_cbranch_scc1 .Lfs7_done
	s_sleep 1
	s_cmp_lt_u32 s11, 0x100000
	s_cbranch_scc1 .Lfs7_loop
.Lfs7_done:
	s_waitcnt vmcnt(0)
.LBB0_1510:
	s_or_b64 exec, exec, s[4:5]
	s_waitcnt lgkmcnt(0)
	s_barrier

.LBB0_1528:
	s_cmp_gt_i32 s83, 13
	s_cselect_b64 s[0:1], -1, 0
	s_and_b64 s[4:5], s[4:5], s[0:1]
	s_andn2_b64 vcc, exec, s[4:5]
	s_cbranch_vccnz .LBB0_1582
	s_waitcnt vmcnt(0)
	s_waitcnt vmcnt(0) lgkmcnt(0)
	s_barrier
	s_and_saveexec_b64 s[4:5], s[38:39]
	s_cbranch_execz .LBB0_1581
	s_add_u32 s98, s98, 1
	v_mov_b32_e32 v1, 0x25f20
	ds_read_b64 v[2:3], v1
	v_readlane_b32 s6, v238, 18
	v_readlane_b32 s7, v238, 19
	s_lshl_b32 s2, s87, 8
	s_addk_i32 s2, 0x1400
	v_mov_b32_e32 v1, s2
	v_mov_b32_e32 v5, 1
	s_nop 1
	global_atomic_add v1, v1, v5, s[6:7] sc0
	buffer_inv sc1
	s_waitcnt vmcnt(1) lgkmcnt(0)
	v_readfirstlane_b32 s12, v1
	v_readfirstlane_b32 s9, v2
	v_readfirstlane_b32 s10, v3
	s_add_u32 s12, s12, 1
	s_mul_i32 s9, s9, s98
	s_mul_i32 s10, s10, s98
	v_mov_b32_e32 v1, 0x3400
	s_cmp_eq_u32 s12, s9
	s_cbranch_scc0 .Lfs8_spin
	buffer_wbl2 sc1
	s_waitcnt vmcnt(0)
	global_atomic_add v1, v5, s[6:7]

.Lfs8_loop:
	global_load_dword v2, v1, s[6:7] sc1
	s_add_u32 s11, s11, 1
	s_waitcnt vmcnt(0)
	v_readfirstlane_b32 s12, v2
	s_cmp_ge_u32 s12, s10
	s_cbranch_scc1 .Lfs8_done
	s_sleep 1
	s_cmp_lt_u32 s11, 0x100000
	s_cbranch_scc1 .Lfs8_loop
.Lfs8_done:
	s_waitcnt vmcnt(0)
.LBB0_1581:
	s_or_b64 exec, exec, s[4:5]
	s_waitcnt lgkmcnt(0)
	s_barrier
